# weight conversion loop (f32 [K][N] to bf16 [N][K] with gain folded) rewritten by hand: 16B loads, next item's loads issued before the current item is processed, same LDS transpose tile; bit-identical
# speedup vs baseline: 1.0107x; 1.0107x over previous
; #define LAS __attribute__((address_space(3)))
; DI int lbid() { int b = (int)blockIdx.x; asm volatile("" : "+s"(b)); return b; }
; DI int lgdim() { int g = (int)gridDim.x; asm volatile("" : "+s"(g)); return g; }
; DI void transpose_item(const float* W, int K, int N, bf16* WT, LAS float* scr, int item, int lane, const float* gk) {
;     const int nblk = N / 32, kb = item / nblk, nb = item % nblk, k0 = 64 * kb, n0 = 32 * nb;
; #pragma unroll
;     for (int i = 0; i < 32; ++i) { const int kk = 2 * i + (lane >> 5); const float gv = gk ? gk[k0 + kk] : 1.0f; scr[kk * 33 + (lane & 31)] = __builtin_nontemporal_load(W + (size_t)(k0 + kk) * N + n0 + (lane & 31)) * gv; }
; DI void prologue(const Params& P, LAS unsigned char* lds) {
;     ...
;     const int gw = lbid() * 8 + wave, NGW = lgdim() * 8;
;     unsigned char* ws = P.ws;
;     constexpr int I0 = 32 * (NIN0 / 32), I1 = 32 * (NIN1 / 32), IO = 32 * 64, IMI = 32 * 256, IMO = 128 * 64, IME = 32 * 32;
;     constexpr int NITEMS = I0 + I1 + 2 * IO + 2 * IMI + 2 * IMO + 2 * IME;
;     for (int it = gw; it < NITEMS; it += NGW) {
;         int q = it;
;         if (q < I0) { transpose_item(P.w_in_ret, D, NIN0, (bf16*)(ws + WS_WIN0), scr, q, lane, P.norm_gain); continue; } q -= I0;
;         if (q < I1) { transpose_item(P.w_in_na, D, NIN1, (bf16*)(ws + WS_WIN1), scr, q, lane, P.norm_gain + 4 * D); continue; } q -= I1;
;         if (q < 2 * IO) { const int i = q / IO; transpose_item(P.w_out + (size_t)i * D * D, D, D, (bf16*)(ws + WS_WOUT) + (size_t)i * D * D, scr, q % IO, lane, nullptr); continue; } q -= 2 * IO;
;         if (q < 2 * IMI) { const int i = q / IMI; transpose_item(P.w_mlp_in + (size_t)i * D * DFF, D, DFF, (bf16*)(ws + WS_WMI) + (size_t)i * D * DFF, scr, q % IMI, lane, P.norm_gain + (size_t)i * 4 * D + 2 * D); continue; } q -= 2 * IMI;
;         if (q < 2 * IMO) { const int i = q / IMO; transpose_item(P.w_mlp_out + (size_t)i * D * DFF, DFF, D, (bf16*)(ws + WS_WMO) + (size_t)i * D * DFF, scr, q % IMO, lane, nullptr); continue; } q -= 2 * IMO;
;         { const int i = q / IME; transpose_item(P.w_mem_kv + (size_t)i * D * 1024, D, 1024, (bf16*)(ws + WS_WMEM) + (size_t)i * D * 1024, scr, q % IME, lane, nullptr); }
.LBB0_6:
	v_mov_b32_e32 v1, v152
	s_load_dwordx16 s[12:27], s[84:85], 0x10
	v_readfirstlane_b32 s0, v1
	s_ashr_i32 s1, s0, 6
	s_mov_b32 s0, s64
	s_lshl_b32 s0, s0, 3
	s_add_i32 s30, s0, s1
	s_waitcnt lgkmcnt(0)
	s_mov_b32 s0, s42
	s_lshl_b32 s34, s0, 3
	s_cmp_gt_i32 s30, 0xc5ff
	v_and_b32_e32 v34, 63, v1
	s_cbranch_scc1 .LBB0_96
	s_load_dwordx2 s[36:37], s[84:85], 0x50
	s_load_dwordx2 s[38:39], s[84:85], 0x60
	v_lshrrev_b32_e32 v2, 3, v34
	v_and_b32_e32 v3, 7, v34
	v_lshrrev_b32_e32 v5, 6, v1
	v_lshlrev_b32_e32 v4, 4, v3
	v_lshlrev_b32_e32 v7, 5, v3
	v_lshlrev_b32_e32 v5, 14, v5
	v_mul_u32_u24_e32 v6, 0x84, v2
	v_mul_u32_u24_e32 v9, 0x420, v3
	v_add_u32_e32 v6, v6, v4
	v_lshl_add_u32 v9, v2, 2, v9
	v_add_u32_e32 v6, v5, v6
	v_add_u32_e32 v9, v5, v9
	v_mov_b32_e32 v5, v6
	v_mov_b32_e32 v6, v9
	s_mov_b32 s53, s30
	s_waitcnt lgkmcnt(0)
	s_cmp_lt_u32 s53, 6656
	s_cbranch_scc1 .Ltr_t0_1
	s_cmp_lt_u32 s53, 11776
	s_cbranch_scc1 .Ltr_t1_1
	s_cmp_lt_u32 s53, 15872
	s_cbranch_scc1 .Ltr_t2_1
	s_cmp_lt_u32 s53, 32256
	s_cbranch_scc1 .Ltr_t3_1
	s_cmp_lt_u32 s53, 48640
	s_cbranch_scc1 .Ltr_t4_1
	s_branch .Ltr_t5_1
.Ltr_t0_1:
	s_mov_b32 s31, s53
	s_mul_i32 s33, s31, 80660
	s_lshr_b32 s33, s33, 24
	s_mul_i32 s35, s33, 208
	s_sub_u32 s35, s31, s35
	s_mul_i32 s46, s33, 1703936
	s_lshl_b32 s47, s35, 7
	s_add_u32 s46, s46, s47
	s_add_u32 s8, s36, s46
	s_addc_u32 s9, s37, 0
	s_mul_i32 s46, s35, 131072
	s_lshl_b32 s47, s33, 7
	s_add_u32 s46, s46, s47
	s_add_u32 s46, s46, 1048576
	s_add_u32 s0, s54, s46
	s_addc_u32 s1, s55, 0
	s_mov_b32 s2, 32768
	s_lshl_b32 s46, s33, 8
	s_add_u32 s46, s46, 0
	s_add_u32 s40, s16, s46
	s_addc_u32 s41, s17, 0
	s_mov_b32 s3, 1
	s_mov_b32 s10, 212992
	v_mul_u32_u24_e32 v77, 26624, v2
	v_lshlrev_b32_e32 v76, 12, v2
	s_branch .Ltr_iss_1
.Ltr_t1_1:
	s_sub_u32 s31, s53, 6656
	s_mul_i32 s33, s31, 104858
	s_lshr_b32 s33, s33, 24
	s_mul_i32 s35, s33, 160
	s_sub_u32 s35, s31, s35
	s_mul_i32 s46, s33, 1310720
	s_lshl_b32 s47, s35, 7
	s_add_u32 s46, s46, s47
	s_add_u32 s8, s38, s46
	s_addc_u32 s9, s39, 0
	s_mul_i32 s46, s35, 131072
	s_lshl_b32 s47, s33, 7
	s_add_u32 s46, s46, s47
	s_add_u32 s46, s46, 28311552
	s_add_u32 s0, s54, s46
	s_addc_u32 s1, s55, 0
	s_mov_b32 s2, 32768
	s_lshl_b32 s46, s33, 8
	s_add_u32 s46, s46, 32768
	s_add_u32 s40, s16, s46
	s_addc_u32 s41, s17, 0
	s_mov_b32 s3, 1
	s_mov_b32 s10, 163840
	v_mul_u32_u24_e32 v77, 20480, v2
	v_lshlrev_b32_e32 v76, 12, v2
	s_branch .Ltr_iss_1
.Ltr_t2_1:
	s_sub_u32 s31, s53, 11776
	s_lshr_b32 s45, s31, 11
	s_and_b32 s31, s31, 2047
	s_lshr_b32 s33, s31, 6
	s_and_b32 s35, s31, 63
	s_mul_i32 s46, s33, 524288
	s_lshl_b32 s47, s35, 7
	s_add_u32 s46, s46, s47
	s_mul_i32 s47, s45, 16777216
	s_add_u32 s46, s46, s47
	s_add_u32 s8, s22, s46
	s_addc_u32 s9, s23, 0
	s_mul_i32 s46, s35, 131072
	s_lshl_b32 s47, s33, 7
	s_add_u32 s46, s46, s47
	s_add_u32 s46, s46, 49283072
	s_mul_i32 s47, s45, 8388608
	s_add_u32 s46, s46, s47
	s_add_u32 s0, s54, s46
	s_addc_u32 s1, s55, 0
	s_mov_b32 s2, 32768
	s_mov_b64 s[40:41], s[16:17]
	s_mov_b32 s3, 0
	s_mov_b32 s10, 65536
	v_mul_u32_u24_e32 v77, 8192, v2
	v_lshlrev_b32_e32 v76, 12, v2
	s_branch .Ltr_iss_1
.Ltr_t3_1:
	s_sub_u32 s31, s53, 15872
	s_lshr_b32 s45, s31, 13
	s_and_b32 s31, s31, 8191
	s_lshr_b32 s33, s31, 8
	s_and_b32 s35, s31, 255
	s_mul_i32 s46, s33, 2097152
	s_lshl_b32 s47, s35, 7
	s_add_u32 s46, s46, s47
	s_mul_i32 s47, s45, 67108864
	s_add_u32 s46, s46, s47
	s_add_u32 s8, s24, s46
	s_addc_u32 s9, s25, 0
	s_mul_i32 s46, s35, 131072
	s_lshl_b32 s47, s33, 7
	s_add_u32 s46, s46, s47
	s_add_u32 s46, s46, 66060288
	s_mul_i32 s47, s45, 33554432
	s_add_u32 s46, s46, s47
	s_add_u32 s0, s54, s46
	s_addc_u32 s1, s55, 0
	s_mov_b32 s2, 32768
	s_lshl_b32 s46, s33, 8
	s_add_u32 s46, s46, 16384
	s_mul_i32 s47, s45, 32768
	s_add_u32 s46, s46, s47
	s_add_u32 s40, s16, s46
	s_addc_u32 s41, s17, 0
	s_mov_b32 s3, 1
	s_mov_b32 s10, 262144
	v_mul_u32_u24_e32 v77, 32768, v2
	v_lshlrev_b32_e32 v76, 12, v2
	s_branch .Ltr_iss_1
.Ltr_t4_1:
	s_sub_u32 s31, s53, 32256
	s_lshr_b32 s45, s31, 13
	s_and_b32 s31, s31, 8191
	s_lshr_b32 s33, s31, 6
	s_and_b32 s35, s31, 63
	s_mul_i32 s46, s33, 524288
	s_lshl_b32 s47, s35, 7
	s_add_u32 s46, s46, s47
	s_mul_i32 s47, s45, 67108864
	s_add_u32 s46, s46, s47
	s_add_u32 s8, s26, s46
	s_addc_u32 s9, s27, 0
	s_mul_i32 s46, s35, 524288
	s_lshl_b32 s47, s33, 7
	s_add_u32 s46, s46, s47
	s_add_u32 s46, s46, 133169152
	s_mul_i32 s47, s45, 33554432
	s_add_u32 s46, s46, s47
	s_add_u32 s0, s54, s46
	s_addc_u32 s1, s55, 0
	s_mov_b32 s2, 131072
	s_mov_b64 s[40:41], s[16:17]
	s_mov_b32 s3, 0
	s_mov_b32 s10, 65536
	v_mul_u32_u24_e32 v77, 8192, v2
	v_lshlrev_b32_e32 v76, 14, v2
	s_branch .Ltr_iss_1
.Ltr_t5_1:
	s_sub_u32 s31, s53, 48640
	s_lshr_b32 s45, s31, 10
	s_and_b32 s31, s31, 1023
	s_lshr_b32 s33, s31, 5
	s_and_b32 s35, s31, 31
	s_mul_i32 s46, s33, 262144
	s_lshl_b32 s47, s35, 7
	s_add_u32 s46, s46, s47
	s_mul_i32 s47, s45, 8388608
	s_add_u32 s46, s46, s47
	s_add_u32 s8, s20, s46
	s_addc_u32 s9, s21, 0
	s_mul_i32 s46, s35, 131072
	s_lshl_b32 s47, s33, 7
	s_add_u32 s46, s46, s47
	s_add_u32 s46, s46, 200278016
	s_mul_i32 s47, s45, 4194304
	s_add_u32 s46, s46, s47
	s_add_u32 s0, s54, s46
	s_addc_u32 s1, s55, 0
	s_mov_b32 s2, 32768
	s_mov_b64 s[40:41], s[16:17]
	s_mov_b32 s3, 0
	s_mov_b32 s10, 32768
	v_mul_u32_u24_e32 v77, 4096, v2
	v_lshlrev_b32_e32 v76, 12, v2
	s_branch .Ltr_iss_1
; DI void transpose_item(const float* W, int K, int N, bf16* WT, LAS float* scr, int item, int lane, const float* gk) {
;     ...
;     for (int i = 0; i < 32; ++i) { const int kk = 2 * i + (lane >> 5); const float gv = gk ? gk[k0 + kk] : 1.0f; scr[kk * 33 + (lane & 31)] = __builtin_nontemporal_load(W + (size_t)(k0 + kk) * N + n0 + (lane & 31)) * gv; }
; DI void prologue(const Params& P, LAS unsigned char* lds) {
;     ...
;     for (int it = gw; it < NITEMS; it += NGW) {
;         int q = it;
;         if (q < I0) { transpose_item(P.w_in_ret, D, NIN0, (bf16*)(ws + WS_WIN0), scr, q, lane, P.norm_gain); continue; } q -= I0;
;         if (q < I1) { transpose_item(P.w_in_na, D, NIN1, (bf16*)(ws + WS_WIN1), scr, q, lane, P.norm_gain + 4 * D); continue; } q -= I1;
;         if (q < 2 * IO) { const int i = q / IO; transpose_item(P.w_out + (size_t)i * D * D, D, D, (bf16*)(ws + WS_WOUT) + (size_t)i * D * D, scr, q % IO, lane, nullptr); continue; } q -= 2 * IO;
;         if (q < 2 * IMI) { const int i = q / IMI; transpose_item(P.w_mlp_in + (size_t)i * D * DFF, D, DFF, (bf16*)(ws + WS_WMI) + (size_t)i * D * DFF, scr, q % IMI, lane, P.norm_gain + (size_t)i * 4 * D + 2 * D); continue; } q -= 2 * IMI;
;         if (q < 2 * IMO) { const int i = q / IMO; transpose_item(P.w_mlp_out + (size_t)i * D * DFF, DFF, D, (bf16*)(ws + WS_WMO) + (size_t)i * D * DFF, scr, q % IMO, lane, nullptr); continue; } q -= 2 * IMO;
;         { const int i = q / IME; transpose_item(P.w_mem_kv + (size_t)i * D * 1024, D, 1024, (bf16*)(ws + WS_WMEM) + (size_t)i * D * 1024, scr, q % IME, lane, nullptr); }
.Ltr_iss_1:
	v_add_u32_e32 v77, v77, v4
	v_add_u32_e32 v76, v76, v4
	global_load_dwordx4 v[36:39], v77, s[8:9] nt
	s_add_u32 s8, s8, s10
	s_addc_u32 s9, s9, 0
	global_load_dwordx4 v[40:43], v77, s[8:9] nt
	s_add_u32 s8, s8, s10
	s_addc_u32 s9, s9, 0
	global_load_dwordx4 v[44:47], v77, s[8:9] nt
	s_add_u32 s8, s8, s10
	s_addc_u32 s9, s9, 0
	global_load_dwordx4 v[48:51], v77, s[8:9] nt
	s_add_u32 s8, s8, s10
	s_addc_u32 s9, s9, 0
	global_load_dwordx4 v[52:55], v77, s[8:9] nt
	s_add_u32 s8, s8, s10
	s_addc_u32 s9, s9, 0
	global_load_dwordx4 v[56:59], v77, s[8:9] nt
	s_add_u32 s8, s8, s10
	s_addc_u32 s9, s9, 0
	global_load_dwordx4 v[60:63], v77, s[8:9] nt
	s_add_u32 s8, s8, s10
	s_addc_u32 s9, s9, 0
	global_load_dwordx4 v[64:67], v77, s[8:9] nt
	global_load_dwordx4 v[68:71], v7, s[40:41]
	global_load_dwordx4 v[72:75], v7, s[40:41] offset:16
	s_waitcnt vmcnt(0)
.Ltr_loop:
	s_add_i32 s52, s53, s34
	s_cmp_lt_i32 s52, 0xc600
	s_cbranch_scc0 .Ltr_lastA
	s_cmp_lt_u32 s52, 6656
	s_cbranch_scc1 .Ltr_t0_2
	s_cmp_lt_u32 s52, 11776
	s_cbranch_scc1 .Ltr_t1_2
	s_cmp_lt_u32 s52, 15872
	s_cbranch_scc1 .Ltr_t2_2
	s_cmp_lt_u32 s52, 32256
	s_cbranch_scc1 .Ltr_t3_2
	s_cmp_lt_u32 s52, 48640
	s_cbranch_scc1 .Ltr_t4_2
	s_branch .Ltr_t5_2
.Ltr_t0_2:
	s_mov_b32 s31, s52
	s_mul_i32 s33, s31, 80660
	s_lshr_b32 s33, s33, 24
	s_mul_i32 s35, s33, 208
	s_sub_u32 s35, s31, s35
	s_mul_i32 s46, s33, 1703936
	s_lshl_b32 s47, s35, 7
	s_add_u32 s46, s46, s47
	s_add_u32 s8, s36, s46
	s_addc_u32 s9, s37, 0
	s_mul_i32 s46, s35, 131072
	s_lshl_b32 s47, s33, 7
	s_add_u32 s46, s46, s47
	s_add_u32 s46, s46, 1048576
	s_add_u32 s4, s54, s46
	s_addc_u32 s5, s55, 0
	s_mov_b32 s6, 32768
	s_lshl_b32 s46, s33, 8
	s_add_u32 s46, s46, 0
	s_add_u32 s40, s16, s46
	s_addc_u32 s41, s17, 0
	s_mov_b32 s7, 1
	s_mov_b32 s10, 212992
	v_mul_u32_u24_e32 v121, 26624, v2
	v_lshlrev_b32_e32 v120, 12, v2
	s_branch .Ltr_iss_2
.Ltr_t1_2:
	s_sub_u32 s31, s52, 6656
	s_mul_i32 s33, s31, 104858
	s_lshr_b32 s33, s33, 24
	s_mul_i32 s35, s33, 160
	s_sub_u32 s35, s31, s35
	s_mul_i32 s46, s33, 1310720
	s_lshl_b32 s47, s35, 7
	s_add_u32 s46, s46, s47
	s_add_u32 s8, s38, s46
	s_addc_u32 s9, s39, 0
	s_mul_i32 s46, s35, 131072
	s_lshl_b32 s47, s33, 7
	s_add_u32 s46, s46, s47
	s_add_u32 s46, s46, 28311552
	s_add_u32 s4, s54, s46
	s_addc_u32 s5, s55, 0
	s_mov_b32 s6, 32768
	s_lshl_b32 s46, s33, 8
	s_add_u32 s46, s46, 32768
	s_add_u32 s40, s16, s46
	s_addc_u32 s41, s17, 0
	s_mov_b32 s7, 1
	s_mov_b32 s10, 163840
	v_mul_u32_u24_e32 v121, 20480, v2
	v_lshlrev_b32_e32 v120, 12, v2
	s_branch .Ltr_iss_2
.Ltr_t2_2:
	s_sub_u32 s31, s52, 11776
	s_lshr_b32 s45, s31, 11
	s_and_b32 s31, s31, 2047
	s_lshr_b32 s33, s31, 6
	s_and_b32 s35, s31, 63
	s_mul_i32 s46, s33, 524288
	s_lshl_b32 s47, s35, 7
	s_add_u32 s46, s46, s47
	s_mul_i32 s47, s45, 16777216
	s_add_u32 s46, s46, s47
	s_add_u32 s8, s22, s46
	s_addc_u32 s9, s23, 0
	s_mul_i32 s46, s35, 131072
	s_lshl_b32 s47, s33, 7
	s_add_u32 s46, s46, s47
	s_add_u32 s46, s46, 49283072
	s_mul_i32 s47, s45, 8388608
	s_add_u32 s46, s46, s47
	s_add_u32 s4, s54, s46
	s_addc_u32 s5, s55, 0
	s_mov_b32 s6, 32768
	s_mov_b64 s[40:41], s[16:17]
	s_mov_b32 s7, 0
	s_mov_b32 s10, 65536
	v_mul_u32_u24_e32 v121, 8192, v2
	v_lshlrev_b32_e32 v120, 12, v2
	s_branch .Ltr_iss_2
.Ltr_t3_2:
	s_sub_u32 s31, s52, 15872
	s_lshr_b32 s45, s31, 13
	s_and_b32 s31, s31, 8191
	s_lshr_b32 s33, s31, 8
	s_and_b32 s35, s31, 255
	s_mul_i32 s46, s33, 2097152
	s_lshl_b32 s47, s35, 7
	s_add_u32 s46, s46, s47
	s_mul_i32 s47, s45, 67108864
	s_add_u32 s46, s46, s47
	s_add_u32 s8, s24, s46
	s_addc_u32 s9, s25, 0
	s_mul_i32 s46, s35, 131072
	s_lshl_b32 s47, s33, 7
	s_add_u32 s46, s46, s47
	s_add_u32 s46, s46, 66060288
	s_mul_i32 s47, s45, 33554432
	s_add_u32 s46, s46, s47
	s_add_u32 s4, s54, s46
	s_addc_u32 s5, s55, 0
	s_mov_b32 s6, 32768
	s_lshl_b32 s46, s33, 8
	s_add_u32 s46, s46, 16384
	s_mul_i32 s47, s45, 32768
	s_add_u32 s46, s46, s47
	s_add_u32 s40, s16, s46
	s_addc_u32 s41, s17, 0
	s_mov_b32 s7, 1
	s_mov_b32 s10, 262144
	v_mul_u32_u24_e32 v121, 32768, v2
	v_lshlrev_b32_e32 v120, 12, v2
	s_branch .Ltr_iss_2
.Ltr_t4_2:
	s_sub_u32 s31, s52, 32256
	s_lshr_b32 s45, s31, 13
	s_and_b32 s31, s31, 8191
	s_lshr_b32 s33, s31, 6
	s_and_b32 s35, s31, 63
	s_mul_i32 s46, s33, 524288
	s_lshl_b32 s47, s35, 7
	s_add_u32 s46, s46, s47
	s_mul_i32 s47, s45, 67108864
	s_add_u32 s46, s46, s47
	s_add_u32 s8, s26, s46
	s_addc_u32 s9, s27, 0
	s_mul_i32 s46, s35, 524288
	s_lshl_b32 s47, s33, 7
	s_add_u32 s46, s46, s47
	s_add_u32 s46, s46, 133169152
	s_mul_i32 s47, s45, 33554432
	s_add_u32 s46, s46, s47
	s_add_u32 s4, s54, s46
	s_addc_u32 s5, s55, 0
	s_mov_b32 s6, 131072
	s_mov_b64 s[40:41], s[16:17]
	s_mov_b32 s7, 0
	s_mov_b32 s10, 65536
	v_mul_u32_u24_e32 v121, 8192, v2
	v_lshlrev_b32_e32 v120, 14, v2
	s_branch .Ltr_iss_2
.Ltr_t5_2:
	s_sub_u32 s31, s52, 48640
	s_lshr_b32 s45, s31, 10
	s_and_b32 s31, s31, 1023
	s_lshr_b32 s33, s31, 5
	s_and_b32 s35, s31, 31
	s_mul_i32 s46, s33, 262144
	s_lshl_b32 s47, s35, 7
	s_add_u32 s46, s46, s47
	s_mul_i32 s47, s45, 8388608
	s_add_u32 s46, s46, s47
	s_add_u32 s8, s20, s46
	s_addc_u32 s9, s21, 0
	s_mul_i32 s46, s35, 131072
	s_lshl_b32 s47, s33, 7
	s_add_u32 s46, s46, s47
	s_add_u32 s46, s46, 200278016
	s_mul_i32 s47, s45, 4194304
	s_add_u32 s46, s46, s47
	s_add_u32 s4, s54, s46
	s_addc_u32 s5, s55, 0
	s_mov_b32 s6, 32768
	s_mov_b64 s[40:41], s[16:17]
	s_mov_b32 s7, 0
	s_mov_b32 s10, 32768
	v_mul_u32_u24_e32 v121, 4096, v2
	v_lshlrev_b32_e32 v120, 12, v2
	s_branch .Ltr_iss_2
; #define LAS __attribute__((address_space(3)))
; DI unsigned pk2(float lo, float hi) { return pg8::cvt_pk_bf16(lo, hi); }
; DI void transpose_item(const float* W, int K, int N, bf16* WT, LAS float* scr, int item, int lane, const float* gk) {
;     const int nblk = N / 32, kb = item / nblk, nb = item % nblk, k0 = 64 * kb, n0 = 32 * nb;
; #pragma unroll
;     for (int i = 0; i < 32; ++i) { const int kk = 2 * i + (lane >> 5); const float gv = gk ? gk[k0 + kk] : 1.0f; scr[kk * 33 + (lane & 31)] = __builtin_nontemporal_load(W + (size_t)(k0 + kk) * N + n0 + (lane & 31)) * gv; }
;     __builtin_amdgcn_fence(__ATOMIC_RELEASE, "workgroup"); asm volatile("s_waitcnt lgkmcnt(0)" ::: "memory");
;     const int c = lane & 7;
; #pragma unroll
;     for (int j = 0; j < 4; ++j) { const int n = (lane >> 3) + 8 * j; const LAS float* s = scr + (8 * c) * 33 + n;
;         v4u o; o.x = pk2(s[0 * 33], s[1 * 33]); o.y = pk2(s[2 * 33], s[3 * 33]); o.z = pk2(s[4 * 33], s[5 * 33]); o.w = pk2(s[6 * 33], s[7 * 33]);
;         *(v4u*)(WT + (size_t)(n0 + n) * K + k0 + 8 * c) = o; }
.Ltr_iss_2:
	v_add_u32_e32 v121, v121, v4
	v_add_u32_e32 v120, v120, v4
	global_load_dwordx4 v[80:83], v121, s[8:9] nt
	s_add_u32 s8, s8, s10
	s_addc_u32 s9, s9, 0
	global_load_dwordx4 v[84:87], v121, s[8:9] nt
	s_add_u32 s8, s8, s10
	s_addc_u32 s9, s9, 0
	global_load_dwordx4 v[88:91], v121, s[8:9] nt
	s_add_u32 s8, s8, s10
	s_addc_u32 s9, s9, 0
	global_load_dwordx4 v[92:95], v121, s[8:9] nt
	s_add_u32 s8, s8, s10
	s_addc_u32 s9, s9, 0
	global_load_dwordx4 v[96:99], v121, s[8:9] nt
	s_add_u32 s8, s8, s10
	s_addc_u32 s9, s9, 0
	global_load_dwordx4 v[100:103], v121, s[8:9] nt
	s_add_u32 s8, s8, s10
	s_addc_u32 s9, s9, 0
	global_load_dwordx4 v[104:107], v121, s[8:9] nt
	s_add_u32 s8, s8, s10
	s_addc_u32 s9, s9, 0
	global_load_dwordx4 v[108:111], v121, s[8:9] nt
	global_load_dwordx4 v[112:115], v7, s[40:41]
	global_load_dwordx4 v[116:119], v7, s[40:41] offset:16
	s_waitcnt vmcnt(14)
	s_cmp_lg_u32 s3, 0
	s_cbranch_scc1 .Ltr_g_3
	v_mov_b32_e32 v68, 1.0
	v_mov_b32_e32 v69, 1.0
	v_mov_b32_e32 v70, 1.0
	v_mov_b32_e32 v71, 1.0
	v_mov_b32_e32 v72, 1.0
	v_mov_b32_e32 v73, 1.0
	v_mov_b32_e32 v74, 1.0
	v_mov_b32_e32 v75, 1.0
.Ltr_g_3:
	ds_write_b32 v5, v36
	ds_write_b32 v5, v37 offset:4
	ds_write_b32 v5, v38 offset:8
	ds_write_b32 v5, v39 offset:12
	ds_write_b32 v5, v40 offset:1056
	ds_write_b32 v5, v41 offset:1060
	ds_write_b32 v5, v42 offset:1064
	ds_write_b32 v5, v43 offset:1068
	ds_write_b32 v5, v44 offset:2112
	ds_write_b32 v5, v45 offset:2116
	ds_write_b32 v5, v46 offset:2120
	ds_write_b32 v5, v47 offset:2124
	ds_write_b32 v5, v48 offset:3168
	ds_write_b32 v5, v49 offset:3172
	ds_write_b32 v5, v50 offset:3176
	ds_write_b32 v5, v51 offset:3180
	ds_write_b32 v5, v52 offset:4224
	ds_write_b32 v5, v53 offset:4228
	ds_write_b32 v5, v54 offset:4232
	ds_write_b32 v5, v55 offset:4236
	ds_write_b32 v5, v56 offset:5280
	ds_write_b32 v5, v57 offset:5284
	ds_write_b32 v5, v58 offset:5288
	ds_write_b32 v5, v59 offset:5292
	ds_write_b32 v5, v60 offset:6336
	ds_write_b32 v5, v61 offset:6340
	ds_write_b32 v5, v62 offset:6344
	ds_write_b32 v5, v63 offset:6348
	ds_write_b32 v5, v64 offset:7392
	ds_write_b32 v5, v65 offset:7396
	ds_write_b32 v5, v66 offset:7400
	ds_write_b32 v5, v67 offset:7404
	s_waitcnt lgkmcnt(0)
	ds_read2_b32 v[8:9], v6 offset0:0 offset1:33
	ds_read2_b32 v[10:11], v6 offset0:66 offset1:99
	ds_read2_b32 v[12:13], v6 offset0:132 offset1:165
	ds_read2_b32 v[14:15], v6 offset0:198 offset1:231
	ds_read2_b32 v[16:17], v6 offset0:8 offset1:41
	ds_read2_b32 v[18:19], v6 offset0:74 offset1:107
	ds_read2_b32 v[20:21], v6 offset0:140 offset1:173
	ds_read2_b32 v[22:23], v6 offset0:206 offset1:239
	ds_read2_b32 v[122:123], v6 offset0:16 offset1:49
	ds_read2_b32 v[124:125], v6 offset0:82 offset1:115
	ds_read2_b32 v[126:127], v6 offset0:148 offset1:181
	ds_read2_b32 v[128:129], v6 offset0:214 offset1:247
	ds_read2_b32 v[130:131], v6 offset0:24 offset1:57
	ds_read2_b32 v[132:133], v6 offset0:90 offset1:123
	ds_read2_b32 v[134:135], v6 offset0:156 offset1:189
	ds_read2_b32 v[136:137], v6 offset0:222 offset1:255
	s_waitcnt lgkmcnt(0)
	v_mul_f32_e32 v8, v8, v68
	v_mul_f32_e32 v9, v9, v69
	v_mul_f32_e32 v10, v10, v70
	v_mul_f32_e32 v11, v11, v71
	v_mul_f32_e32 v12, v12, v72
	v_mul_f32_e32 v13, v13, v73
	v_mul_f32_e32 v14, v14, v74
	v_mul_f32_e32 v15, v15, v75
	v_cvt_pk_bf16_f32 v24, v8, v9
	v_cvt_pk_bf16_f32 v25, v10, v11
	v_cvt_pk_bf16_f32 v26, v12, v13
	v_cvt_pk_bf16_f32 v27, v14, v15
	global_store_dwordx4 v76, v[24:27], s[0:1]
	v_add_u32_e32 v76, s2, v76
	v_mul_f32_e32 v16, v16, v68
	v_mul_f32_e32 v17, v17, v69
	v_mul_f32_e32 v18, v18, v70
	v_mul_f32_e32 v19, v19, v71
	v_mul_f32_e32 v20, v20, v72
	v_mul_f32_e32 v21, v21, v73
	v_mul_f32_e32 v22, v22, v74
	v_mul_f32_e32 v23, v23, v75
	v_cvt_pk_bf16_f32 v28, v16, v17
	v_cvt_pk_bf16_f32 v29, v18, v19
	v_cvt_pk_bf16_f32 v30, v20, v21
	v_cvt_pk_bf16_f32 v31, v22, v23
	global_store_dwordx4 v76, v[28:31], s[0:1]
	v_add_u32_e32 v76, s2, v76
	v_mul_f32_e32 v122, v122, v68
	v_mul_f32_e32 v123, v123, v69
	v_mul_f32_e32 v124, v124, v70
	v_mul_f32_e32 v125, v125, v71
	v_mul_f32_e32 v126, v126, v72
	v_mul_f32_e32 v127, v127, v73
	v_mul_f32_e32 v128, v128, v74
	v_mul_f32_e32 v129, v129, v75
	v_cvt_pk_bf16_f32 v24, v122, v123
	v_cvt_pk_bf16_f32 v25, v124, v125
	v_cvt_pk_bf16_f32 v26, v126, v127
	v_cvt_pk_bf16_f32 v27, v128, v129
	global_store_dwordx4 v76, v[24:27], s[0:1]
	v_add_u32_e32 v76, s2, v76
	v_mul_f32_e32 v130, v130, v68
	v_mul_f32_e32 v131, v131, v69
	v_mul_f32_e32 v132, v132, v70
	v_mul_f32_e32 v133, v133, v71
	v_mul_f32_e32 v134, v134, v72
	v_mul_f32_e32 v135, v135, v73
	v_mul_f32_e32 v136, v136, v74
	v_mul_f32_e32 v137, v137, v75
	v_cvt_pk_bf16_f32 v28, v130, v131
	v_cvt_pk_bf16_f32 v29, v132, v133
	v_cvt_pk_bf16_f32 v30, v134, v135
	v_cvt_pk_bf16_f32 v31, v136, v137
	global_store_dwordx4 v76, v[28:31], s[0:1]
	s_add_i32 s53, s52, s34
	s_cmp_lt_i32 s53, 0xc600
	s_cbranch_scc0 .Ltr_lastB
	s_cmp_lt_u32 s53, 6656
	s_cbranch_scc1 .Ltr_t0_4
	s_cmp_lt_u32 s53, 11776
	s_cbranch_scc1 .Ltr_t1_4
	s_cmp_lt_u32 s53, 15872
	s_cbranch_scc1 .Ltr_t2_4
	s_cmp_lt_u32 s53, 32256
	s_cbranch_scc1 .Ltr_t3_4
	s_cmp_lt_u32 s53, 48640
	s_cbranch_scc1 .Ltr_t4_4
	s_branch .Ltr_t5_4

; #define LAS __attribute__((address_space(3)))
; DI unsigned pk2(float lo, float hi) { return pg8::cvt_pk_bf16(lo, hi); }
; DI void transpose_item(const float* W, int K, int N, bf16* WT, LAS float* scr, int item, int lane, const float* gk) {
;     const int nblk = N / 32, kb = item / nblk, nb = item % nblk, k0 = 64 * kb, n0 = 32 * nb;
; #pragma unroll
;     for (int i = 0; i < 32; ++i) { const int kk = 2 * i + (lane >> 5); const float gv = gk ? gk[k0 + kk] : 1.0f; scr[kk * 33 + (lane & 31)] = __builtin_nontemporal_load(W + (size_t)(k0 + kk) * N + n0 + (lane & 31)) * gv; }
;     __builtin_amdgcn_fence(__ATOMIC_RELEASE, "workgroup"); asm volatile("s_waitcnt lgkmcnt(0)" ::: "memory");
;     const int c = lane & 7;
; #pragma unroll
;     for (int j = 0; j < 4; ++j) { const int n = (lane >> 3) + 8 * j; const LAS float* s = scr + (8 * c) * 33 + n;
;         v4u o; o.x = pk2(s[0 * 33], s[1 * 33]); o.y = pk2(s[2 * 33], s[3 * 33]); o.z = pk2(s[4 * 33], s[5 * 33]); o.w = pk2(s[6 * 33], s[7 * 33]);
;         *(v4u*)(WT + (size_t)(n0 + n) * K + k0 + 8 * c) = o; }
.Ltr_iss_4:
	v_add_u32_e32 v77, v77, v4
	v_add_u32_e32 v76, v76, v4
	global_load_dwordx4 v[36:39], v77, s[8:9] nt
	s_add_u32 s8, s8, s10
	s_addc_u32 s9, s9, 0
	global_load_dwordx4 v[40:43], v77, s[8:9] nt
	s_add_u32 s8, s8, s10
	s_addc_u32 s9, s9, 0
	global_load_dwordx4 v[44:47], v77, s[8:9] nt
	s_add_u32 s8, s8, s10
	s_addc_u32 s9, s9, 0
	global_load_dwordx4 v[48:51], v77, s[8:9] nt
	s_add_u32 s8, s8, s10
	s_addc_u32 s9, s9, 0
	global_load_dwordx4 v[52:55], v77, s[8:9] nt
	s_add_u32 s8, s8, s10
	s_addc_u32 s9, s9, 0
	global_load_dwordx4 v[56:59], v77, s[8:9] nt
	s_add_u32 s8, s8, s10
	s_addc_u32 s9, s9, 0
	global_load_dwordx4 v[60:63], v77, s[8:9] nt
	s_add_u32 s8, s8, s10
	s_addc_u32 s9, s9, 0
	global_load_dwordx4 v[64:67], v77, s[8:9] nt
	global_load_dwordx4 v[68:71], v7, s[40:41]
	global_load_dwordx4 v[72:75], v7, s[40:41] offset:16
	s_waitcnt vmcnt(14)
	s_cmp_lg_u32 s7, 0
	s_cbranch_scc1 .Ltr_g_5
	v_mov_b32_e32 v112, 1.0
	v_mov_b32_e32 v113, 1.0
	v_mov_b32_e32 v114, 1.0
	v_mov_b32_e32 v115, 1.0
	v_mov_b32_e32 v116, 1.0
	v_mov_b32_e32 v117, 1.0
	v_mov_b32_e32 v118, 1.0
	v_mov_b32_e32 v119, 1.0
.Ltr_g_5:
	ds_write_b32 v5, v80
	ds_write_b32 v5, v81 offset:4
	ds_write_b32 v5, v82 offset:8
	ds_write_b32 v5, v83 offset:12
	ds_write_b32 v5, v84 offset:1056
	ds_write_b32 v5, v85 offset:1060
	ds_write_b32 v5, v86 offset:1064
	ds_write_b32 v5, v87 offset:1068
	ds_write_b32 v5, v88 offset:2112
	ds_write_b32 v5, v89 offset:2116
	ds_write_b32 v5, v90 offset:2120
	ds_write_b32 v5, v91 offset:2124
	ds_write_b32 v5, v92 offset:3168
	ds_write_b32 v5, v93 offset:3172
	ds_write_b32 v5, v94 offset:3176
	ds_write_b32 v5, v95 offset:3180
	ds_write_b32 v5, v96 offset:4224
	ds_write_b32 v5, v97 offset:4228
	ds_write_b32 v5, v98 offset:4232
	ds_write_b32 v5, v99 offset:4236
	ds_write_b32 v5, v100 offset:5280
	ds_write_b32 v5, v101 offset:5284
	ds_write_b32 v5, v102 offset:5288
	ds_write_b32 v5, v103 offset:5292
	ds_write_b32 v5, v104 offset:6336
	ds_write_b32 v5, v105 offset:6340
	ds_write_b32 v5, v106 offset:6344
	ds_write_b32 v5, v107 offset:6348
	ds_write_b32 v5, v108 offset:7392
	ds_write_b32 v5, v109 offset:7396
	ds_write_b32 v5, v110 offset:7400
	ds_write_b32 v5, v111 offset:7404
	s_waitcnt lgkmcnt(0)
	ds_read2_b32 v[8:9], v6 offset0:0 offset1:33
	ds_read2_b32 v[10:11], v6 offset0:66 offset1:99
	ds_read2_b32 v[12:13], v6 offset0:132 offset1:165
	ds_read2_b32 v[14:15], v6 offset0:198 offset1:231
	ds_read2_b32 v[16:17], v6 offset0:8 offset1:41
	ds_read2_b32 v[18:19], v6 offset0:74 offset1:107
	ds_read2_b32 v[20:21], v6 offset0:140 offset1:173
	ds_read2_b32 v[22:23], v6 offset0:206 offset1:239
	ds_read2_b32 v[122:123], v6 offset0:16 offset1:49
	ds_read2_b32 v[124:125], v6 offset0:82 offset1:115
	ds_read2_b32 v[126:127], v6 offset0:148 offset1:181
	ds_read2_b32 v[128:129], v6 offset0:214 offset1:247
	ds_read2_b32 v[130:131], v6 offset0:24 offset1:57
	ds_read2_b32 v[132:133], v6 offset0:90 offset1:123
	ds_read2_b32 v[134:135], v6 offset0:156 offset1:189
	ds_read2_b32 v[136:137], v6 offset0:222 offset1:255
	s_waitcnt lgkmcnt(0)
	v_mul_f32_e32 v8, v8, v112
	v_mul_f32_e32 v9, v9, v113
	v_mul_f32_e32 v10, v10, v114
	v_mul_f32_e32 v11, v11, v115
	v_mul_f32_e32 v12, v12, v116
	v_mul_f32_e32 v13, v13, v117
	v_mul_f32_e32 v14, v14, v118
	v_mul_f32_e32 v15, v15, v119
	v_cvt_pk_bf16_f32 v24, v8, v9
	v_cvt_pk_bf16_f32 v25, v10, v11
	v_cvt_pk_bf16_f32 v26, v12, v13
	v_cvt_pk_bf16_f32 v27, v14, v15
	global_store_dwordx4 v120, v[24:27], s[4:5]
	v_add_u32_e32 v120, s6, v120
	v_mul_f32_e32 v16, v16, v112
	v_mul_f32_e32 v17, v17, v113
	v_mul_f32_e32 v18, v18, v114
	v_mul_f32_e32 v19, v19, v115
	v_mul_f32_e32 v20, v20, v116
	v_mul_f32_e32 v21, v21, v117
	v_mul_f32_e32 v22, v22, v118
	v_mul_f32_e32 v23, v23, v119
	v_cvt_pk_bf16_f32 v28, v16, v17
	v_cvt_pk_bf16_f32 v29, v18, v19
	v_cvt_pk_bf16_f32 v30, v20, v21
	v_cvt_pk_bf16_f32 v31, v22, v23
	global_store_dwordx4 v120, v[28:31], s[4:5]
	v_add_u32_e32 v120, s6, v120
	v_mul_f32_e32 v122, v122, v112
	v_mul_f32_e32 v123, v123, v113
	v_mul_f32_e32 v124, v124, v114
	v_mul_f32_e32 v125, v125, v115
	v_mul_f32_e32 v126, v126, v116
	v_mul_f32_e32 v127, v127, v117
	v_mul_f32_e32 v128, v128, v118
	v_mul_f32_e32 v129, v129, v119
	v_cvt_pk_bf16_f32 v24, v122, v123
	v_cvt_pk_bf16_f32 v25, v124, v125
	v_cvt_pk_bf16_f32 v26, v126, v127
	v_cvt_pk_bf16_f32 v27, v128, v129
	global_store_dwordx4 v120, v[24:27], s[4:5]
	v_add_u32_e32 v120, s6, v120
	v_mul_f32_e32 v130, v130, v112
	v_mul_f32_e32 v131, v131, v113
	v_mul_f32_e32 v132, v132, v114
	v_mul_f32_e32 v133, v133, v115
	v_mul_f32_e32 v134, v134, v116
	v_mul_f32_e32 v135, v135, v117
	v_mul_f32_e32 v136, v136, v118
	v_mul_f32_e32 v137, v137, v119
	v_cvt_pk_bf16_f32 v28, v130, v131
	v_cvt_pk_bf16_f32 v29, v132, v133
	v_cvt_pk_bf16_f32 v30, v134, v135
	v_cvt_pk_bf16_f32 v31, v136, v137
	global_store_dwordx4 v120, v[28:31], s[4:5]
	s_branch .Ltr_loop
.Ltr_lastA:
	s_waitcnt vmcnt(4)
	s_cmp_lg_u32 s3, 0
	s_cbranch_scc1 .Ltr_g_6
	v_mov_b32_e32 v68, 1.0
	v_mov_b32_e32 v69, 1.0
	v_mov_b32_e32 v70, 1.0
	v_mov_b32_e32 v71, 1.0
	v_mov_b32_e32 v72, 1.0
	v_mov_b32_e32 v73, 1.0
	v_mov_b32_e32 v74, 1.0
	v_mov_b32_e32 v75, 1.0
; #define LAS __attribute__((address_space(3)))
; DI unsigned pk2(float lo, float hi) { return pg8::cvt_pk_bf16(lo, hi); }
; DI void transpose_item(const float* W, int K, int N, bf16* WT, LAS float* scr, int item, int lane, const float* gk) {
;     ...
;     for (int i = 0; i < 32; ++i) { const int kk = 2 * i + (lane >> 5); const float gv = gk ? gk[k0 + kk] : 1.0f; scr[kk * 33 + (lane & 31)] = __builtin_nontemporal_load(W + (size_t)(k0 + kk) * N + n0 + (lane & 31)) * gv; }
;     __builtin_amdgcn_fence(__ATOMIC_RELEASE, "workgroup"); asm volatile("s_waitcnt lgkmcnt(0)" ::: "memory");
;     const int c = lane & 7;
; #pragma unroll
;     for (int j = 0; j < 4; ++j) { const int n = (lane >> 3) + 8 * j; const LAS float* s = scr + (8 * c) * 33 + n;
;         v4u o; o.x = pk2(s[0 * 33], s[1 * 33]); o.y = pk2(s[2 * 33], s[3 * 33]); o.z = pk2(s[4 * 33], s[5 * 33]); o.w = pk2(s[6 * 33], s[7 * 33]);
;         *(v4u*)(WT + (size_t)(n0 + n) * K + k0 + 8 * c) = o; }
.Ltr_g_6:
	ds_write_b32 v5, v36
	ds_write_b32 v5, v37 offset:4
	ds_write_b32 v5, v38 offset:8
	ds_write_b32 v5, v39 offset:12
	ds_write_b32 v5, v40 offset:1056
	ds_write_b32 v5, v41 offset:1060
	ds_write_b32 v5, v42 offset:1064
	ds_write_b32 v5, v43 offset:1068
	ds_write_b32 v5, v44 offset:2112
	ds_write_b32 v5, v45 offset:2116
	ds_write_b32 v5, v46 offset:2120
	ds_write_b32 v5, v47 offset:2124
	ds_write_b32 v5, v48 offset:3168
	ds_write_b32 v5, v49 offset:3172
	ds_write_b32 v5, v50 offset:3176
	ds_write_b32 v5, v51 offset:3180
	ds_write_b32 v5, v52 offset:4224
	ds_write_b32 v5, v53 offset:4228
	ds_write_b32 v5, v54 offset:4232
	ds_write_b32 v5, v55 offset:4236
	ds_write_b32 v5, v56 offset:5280
	ds_write_b32 v5, v57 offset:5284
	ds_write_b32 v5, v58 offset:5288
	ds_write_b32 v5, v59 offset:5292
	ds_write_b32 v5, v60 offset:6336
	ds_write_b32 v5, v61 offset:6340
	ds_write_b32 v5, v62 offset:6344
	ds_write_b32 v5, v63 offset:6348
	ds_write_b32 v5, v64 offset:7392
	ds_write_b32 v5, v65 offset:7396
	ds_write_b32 v5, v66 offset:7400
	ds_write_b32 v5, v67 offset:7404
	s_waitcnt lgkmcnt(0)
	ds_read2_b32 v[8:9], v6 offset0:0 offset1:33
	ds_read2_b32 v[10:11], v6 offset0:66 offset1:99
	ds_read2_b32 v[12:13], v6 offset0:132 offset1:165
	ds_read2_b32 v[14:15], v6 offset0:198 offset1:231
	ds_read2_b32 v[16:17], v6 offset0:8 offset1:41
	ds_read2_b32 v[18:19], v6 offset0:74 offset1:107
	ds_read2_b32 v[20:21], v6 offset0:140 offset1:173
	ds_read2_b32 v[22:23], v6 offset0:206 offset1:239
	ds_read2_b32 v[122:123], v6 offset0:16 offset1:49
	ds_read2_b32 v[124:125], v6 offset0:82 offset1:115
	ds_read2_b32 v[126:127], v6 offset0:148 offset1:181
	ds_read2_b32 v[128:129], v6 offset0:214 offset1:247
	ds_read2_b32 v[130:131], v6 offset0:24 offset1:57
	ds_read2_b32 v[132:133], v6 offset0:90 offset1:123
	ds_read2_b32 v[134:135], v6 offset0:156 offset1:189
	ds_read2_b32 v[136:137], v6 offset0:222 offset1:255
	s_waitcnt lgkmcnt(0)
	v_mul_f32_e32 v8, v8, v68
	v_mul_f32_e32 v9, v9, v69
	v_mul_f32_e32 v10, v10, v70
	v_mul_f32_e32 v11, v11, v71
	v_mul_f32_e32 v12, v12, v72
	v_mul_f32_e32 v13, v13, v73
	v_mul_f32_e32 v14, v14, v74
	v_mul_f32_e32 v15, v15, v75
	v_cvt_pk_bf16_f32 v24, v8, v9
	v_cvt_pk_bf16_f32 v25, v10, v11
	v_cvt_pk_bf16_f32 v26, v12, v13
	v_cvt_pk_bf16_f32 v27, v14, v15
	global_store_dwordx4 v76, v[24:27], s[0:1]
	v_add_u32_e32 v76, s2, v76
	v_mul_f32_e32 v16, v16, v68
	v_mul_f32_e32 v17, v17, v69
	v_mul_f32_e32 v18, v18, v70
	v_mul_f32_e32 v19, v19, v71
	v_mul_f32_e32 v20, v20, v72
	v_mul_f32_e32 v21, v21, v73
	v_mul_f32_e32 v22, v22, v74
	v_mul_f32_e32 v23, v23, v75
	v_cvt_pk_bf16_f32 v28, v16, v17
	v_cvt_pk_bf16_f32 v29, v18, v19
	v_cvt_pk_bf16_f32 v30, v20, v21
	v_cvt_pk_bf16_f32 v31, v22, v23
	global_store_dwordx4 v76, v[28:31], s[0:1]
	v_add_u32_e32 v76, s2, v76
	v_mul_f32_e32 v122, v122, v68
	v_mul_f32_e32 v123, v123, v69
	v_mul_f32_e32 v124, v124, v70
	v_mul_f32_e32 v125, v125, v71
	v_mul_f32_e32 v126, v126, v72
	v_mul_f32_e32 v127, v127, v73
	v_mul_f32_e32 v128, v128, v74
	v_mul_f32_e32 v129, v129, v75
	v_cvt_pk_bf16_f32 v24, v122, v123
	v_cvt_pk_bf16_f32 v25, v124, v125
	v_cvt_pk_bf16_f32 v26, v126, v127
	v_cvt_pk_bf16_f32 v27, v128, v129
	global_store_dwordx4 v76, v[24:27], s[0:1]
	v_add_u32_e32 v76, s2, v76
	v_mul_f32_e32 v130, v130, v68
	v_mul_f32_e32 v131, v131, v69
	v_mul_f32_e32 v132, v132, v70
	v_mul_f32_e32 v133, v133, v71
	v_mul_f32_e32 v134, v134, v72
	v_mul_f32_e32 v135, v135, v73
	v_mul_f32_e32 v136, v136, v74
	v_mul_f32_e32 v137, v137, v75
	v_cvt_pk_bf16_f32 v28, v130, v131
	v_cvt_pk_bf16_f32 v29, v132, v133
	v_cvt_pk_bf16_f32 v30, v134, v135
	v_cvt_pk_bf16_f32 v31, v136, v137
	global_store_dwordx4 v76, v[28:31], s[0:1]
	s_branch .Ltr_done
.Ltr_lastB:
	s_waitcnt vmcnt(4)
	s_cmp_lg_u32 s7, 0
	s_cbranch_scc1 .Ltr_g_7
	v_mov_b32_e32 v112, 1.0
	v_mov_b32_e32 v113, 1.0
	v_mov_b32_e32 v114, 1.0
	v_mov_b32_e32 v115, 1.0
	v_mov_b32_e32 v116, 1.0
	v_mov_b32_e32 v117, 1.0
	v_mov_b32_e32 v118, 1.0
	v_mov_b32_e32 v119, 1.0
; #define LAS __attribute__((address_space(3)))
; DI unsigned pk2(float lo, float hi) { return pg8::cvt_pk_bf16(lo, hi); }
; DI int lbid() { int b = (int)blockIdx.x; asm volatile("" : "+s"(b)); return b; }
; DI int lgdim() { int g = (int)gridDim.x; asm volatile("" : "+s"(g)); return g; }
; DI void transpose_item(const float* W, int K, int N, bf16* WT, LAS float* scr, int item, int lane, const float* gk) {
;     ...
;     for (int i = 0; i < 32; ++i) { const int kk = 2 * i + (lane >> 5); const float gv = gk ? gk[k0 + kk] : 1.0f; scr[kk * 33 + (lane & 31)] = __builtin_nontemporal_load(W + (size_t)(k0 + kk) * N + n0 + (lane & 31)) * gv; }
;     __builtin_amdgcn_fence(__ATOMIC_RELEASE, "workgroup"); asm volatile("s_waitcnt lgkmcnt(0)" ::: "memory");
;     const int c = lane & 7;
; #pragma unroll
;     for (int j = 0; j < 4; ++j) { const int n = (lane >> 3) + 8 * j; const LAS float* s = scr + (8 * c) * 33 + n;
;         v4u o; o.x = pk2(s[0 * 33], s[1 * 33]); o.y = pk2(s[2 * 33], s[3 * 33]); o.z = pk2(s[4 * 33], s[5 * 33]); o.w = pk2(s[6 * 33], s[7 * 33]);
;         *(v4u*)(WT + (size_t)(n0 + n) * K + k0 + 8 * c) = o; }
; DI void prologue(const Params& P, LAS unsigned char* lds) {
;     ...
;     float* rc = (float*)(ws + WS_ROPE); float* rs = rc + 8192 * 64;
;     for (int idx = lbid() * 512 + tid; idx < 8192 * 64; idx += lgdim() * 512) {
;         const int pos = idx >> 6, i = idx & 63;
;         const float inv = powf(10000.0f, -(float)i / 64.0f);
;         const float ang = (float)pos * inv;
;         rc[idx] = cosf(ang); rs[idx] = sinf(ang);
;     }
.Ltr_g_7:
	ds_write_b32 v5, v80
	ds_write_b32 v5, v81 offset:4
	ds_write_b32 v5, v82 offset:8
	ds_write_b32 v5, v83 offset:12
	ds_write_b32 v5, v84 offset:1056
	ds_write_b32 v5, v85 offset:1060
	ds_write_b32 v5, v86 offset:1064
	ds_write_b32 v5, v87 offset:1068
	ds_write_b32 v5, v88 offset:2112
	ds_write_b32 v5, v89 offset:2116
	ds_write_b32 v5, v90 offset:2120
	ds_write_b32 v5, v91 offset:2124
	ds_write_b32 v5, v92 offset:3168
	ds_write_b32 v5, v93 offset:3172
	ds_write_b32 v5, v94 offset:3176
	ds_write_b32 v5, v95 offset:3180
	ds_write_b32 v5, v96 offset:4224
	ds_write_b32 v5, v97 offset:4228
	ds_write_b32 v5, v98 offset:4232
	ds_write_b32 v5, v99 offset:4236
	ds_write_b32 v5, v100 offset:5280
	ds_write_b32 v5, v101 offset:5284
	ds_write_b32 v5, v102 offset:5288
	ds_write_b32 v5, v103 offset:5292
	ds_write_b32 v5, v104 offset:6336
	ds_write_b32 v5, v105 offset:6340
	ds_write_b32 v5, v106 offset:6344
	ds_write_b32 v5, v107 offset:6348
	ds_write_b32 v5, v108 offset:7392
	ds_write_b32 v5, v109 offset:7396
	ds_write_b32 v5, v110 offset:7400
	ds_write_b32 v5, v111 offset:7404
	s_waitcnt lgkmcnt(0)
	ds_read2_b32 v[8:9], v6 offset0:0 offset1:33
	ds_read2_b32 v[10:11], v6 offset0:66 offset1:99
	ds_read2_b32 v[12:13], v6 offset0:132 offset1:165
	ds_read2_b32 v[14:15], v6 offset0:198 offset1:231
	ds_read2_b32 v[16:17], v6 offset0:8 offset1:41
	ds_read2_b32 v[18:19], v6 offset0:74 offset1:107
	ds_read2_b32 v[20:21], v6 offset0:140 offset1:173
	ds_read2_b32 v[22:23], v6 offset0:206 offset1:239
	ds_read2_b32 v[122:123], v6 offset0:16 offset1:49
	ds_read2_b32 v[124:125], v6 offset0:82 offset1:115
	ds_read2_b32 v[126:127], v6 offset0:148 offset1:181
	ds_read2_b32 v[128:129], v6 offset0:214 offset1:247
	ds_read2_b32 v[130:131], v6 offset0:24 offset1:57
	ds_read2_b32 v[132:133], v6 offset0:90 offset1:123
	ds_read2_b32 v[134:135], v6 offset0:156 offset1:189
	ds_read2_b32 v[136:137], v6 offset0:222 offset1:255
	s_waitcnt lgkmcnt(0)
	v_mul_f32_e32 v8, v8, v112
	v_mul_f32_e32 v9, v9, v113
	v_mul_f32_e32 v10, v10, v114
	v_mul_f32_e32 v11, v11, v115
	v_mul_f32_e32 v12, v12, v116
	v_mul_f32_e32 v13, v13, v117
	v_mul_f32_e32 v14, v14, v118
	v_mul_f32_e32 v15, v15, v119
	v_cvt_pk_bf16_f32 v24, v8, v9
	v_cvt_pk_bf16_f32 v25, v10, v11
	v_cvt_pk_bf16_f32 v26, v12, v13
	v_cvt_pk_bf16_f32 v27, v14, v15
	global_store_dwordx4 v120, v[24:27], s[4:5]
	v_add_u32_e32 v120, s6, v120
	v_mul_f32_e32 v16, v16, v112
	v_mul_f32_e32 v17, v17, v113
	v_mul_f32_e32 v18, v18, v114
	v_mul_f32_e32 v19, v19, v115
	v_mul_f32_e32 v20, v20, v116
	v_mul_f32_e32 v21, v21, v117
	v_mul_f32_e32 v22, v22, v118
	v_mul_f32_e32 v23, v23, v119
	v_cvt_pk_bf16_f32 v28, v16, v17
	v_cvt_pk_bf16_f32 v29, v18, v19
	v_cvt_pk_bf16_f32 v30, v20, v21
	v_cvt_pk_bf16_f32 v31, v22, v23
	global_store_dwordx4 v120, v[28:31], s[4:5]
	v_add_u32_e32 v120, s6, v120
	v_mul_f32_e32 v122, v122, v112
	v_mul_f32_e32 v123, v123, v113
	v_mul_f32_e32 v124, v124, v114
	v_mul_f32_e32 v125, v125, v115
	v_mul_f32_e32 v126, v126, v116
	v_mul_f32_e32 v127, v127, v117
	v_mul_f32_e32 v128, v128, v118
	v_mul_f32_e32 v129, v129, v119
	v_cvt_pk_bf16_f32 v24, v122, v123
	v_cvt_pk_bf16_f32 v25, v124, v125
	v_cvt_pk_bf16_f32 v26, v126, v127
	v_cvt_pk_bf16_f32 v27, v128, v129
	global_store_dwordx4 v120, v[24:27], s[4:5]
	v_add_u32_e32 v120, s6, v120
	v_mul_f32_e32 v130, v130, v112
	v_mul_f32_e32 v131, v131, v113
	v_mul_f32_e32 v132, v132, v114
	v_mul_f32_e32 v133, v133, v115
	v_mul_f32_e32 v134, v134, v116
	v_mul_f32_e32 v135, v135, v117
	v_mul_f32_e32 v136, v136, v118
	v_mul_f32_e32 v137, v137, v119
	v_cvt_pk_bf16_f32 v28, v130, v131
	v_cvt_pk_bf16_f32 v29, v132, v133
	v_cvt_pk_bf16_f32 v30, v134, v135
	v_cvt_pk_bf16_f32 v31, v136, v137
	global_store_dwordx4 v120, v[28:31], s[4:5]
.Ltr_done:
.LBB0_96:
	s_mov_b32 s0, s64
	s_nop 0
	v_lshl_add_u32 v2, s0, 9, v1
	s_mov_b32 s0, 0x80000
	v_cmp_gt_i32_e32 vcc, s0, v2
	s_and_saveexec_b64 s[16:17], vcc
	s_cbranch_execz .LBB0_107
	s_add_u32 s20, s54, 0x10300000
	s_addc_u32 s21, s55, 0
	s_add_u32 s22, s54, 0x10500000
	s_addc_u32 s23, s55, 0
	s_mov_b64 s[24:25], 0
	v_mov_b32_e32 v1, 0x461c4000
	s_mov_b32 s0, 0x3f2aaaab
	v_mov_b32_e32 v6, 0x3e91f4c4
	s_mov_b32 s1, 0x3f317218
	s_movk_i32 s2, 0x204
	s_mov_b32 s3, 0x7f800000
	s_mov_b32 s31, 0x42b17218
	v_mov_b32_e32 v7, 0x37000000
	s_mov_b32 s33, 0x3fb8aa3b
	s_mov_b32 s35, 0xc2ce8ed0
	v_mov_b32_e32 v8, 0x7f800000
	s_brev_b32 s36, 18
	s_mov_b32 s37, 0xfe5163ab
	v_mov_b32_e32 v5, 0
	s_mov_b32 s38, 0x3c439041
	s_mov_b32 s39, 0xdb629599
	s_mov_b32 s40, 0xf534ddc0
	s_mov_b32 s41, 0xfc2757d1
	s_mov_b32 s45, 0x4e441529
	s_mov_b32 s46, 0xa2f9836e
	s_mov_b32 s47, 0x3fc90fda
	s_mov_b32 s48, 0x3f22f983
	s_mov_b32 s49, 0xbfc90fda
	v_mov_b32_e32 v9, 0x3c0881c4
	v_mov_b32_e32 v10, 0xbab64f3b
	s_brev_b32 s50, 1
	s_movk_i32 s51, 0x1f8
	s_mov_b32 s52, 0x7ffff
	v_not_b32_e32 v11, 63
	v_not_b32_e32 v12, 31
	v_mov_b32_e32 v13, 0x7fc00000
	s_branch .LBB0_99
